# M1: next item's K/V rows and gates touched by throw-away loads during the current item's MFMA/store half (L2 prefetch)
# baseline (speedup 1.0000x reference)
.LBB0_377:
	s_or_b64 exec, exec, s[0:1]
	v_add3_u32 v5, v64, v112, v65
	ds_write_b128 v5, v[0:3] offset:17280
	v_lshrrev_b32_e32 v0, 2, v67
	v_and_b32_e32 v98, 8, v0
	v_lshlrev_b32_e32 v0, 5, v68
	v_and_b32_e32 v0, 32, v0
	v_add_u32_e32 v2, v105, v0
	v_lshlrev_b32_e32 v0, 3, v104
	s_waitcnt lgkmcnt(1)
	v_lshrrev_b32_e32 v4, 2, v69
	v_and_b32_e32 v3, 24, v0
	v_lshlrev_b64 v[0:1], 15, v[96:97]
	v_lshl_add_u64 v[100:101], s[2:3], 0, v[0:1]
	v_or_b32_e32 v0, v98, v4
	v_mul_u32_u24_e32 v0, 0x120, v0
	v_add3_u32 v106, v2, v3, v0
	v_lshl_add_u32 v102, v99, 7, v106
	s_waitcnt lgkmcnt(0)
	s_barrier
	s_add_i32 s6, s12, s13
	s_cmp_ge_i32 s6, s14
	s_cbranch_scc1 .Lm1pf_done
	s_lshr_b32 s7, s6, 7
	s_lshl_b32 s7, s7, 13
	s_and_b32 s8, s6, 0x7f
	s_lshl_b32 s8, s8, 6
	s_or_b32 s7, s7, s8
	s_mul_i32 s8, s7, 0x1c00
	s_add_i32 s8, s8, 0x6000000
	s_add_u32 s8, s2, s8
	s_addc_u32 s9, s3, 0
	s_lshl_b32 s10, s7, 4
	s_add_u32 s10, s2, s10
	s_addc_u32 s11, s3, 0
	s_add_u32 s20, s10, 0x80000
	s_addc_u32 s21, s11, 0
	v_and_b32_e32 v154, 64, v104
	v_lshlrev_b32_e32 v154, 4, v154
	v_add_u32_e32 v154, 0x1000, v154
	v_and_b32_e32 v155, 0xffffff80, v104
	v_lshl_add_u32 v154, v155, 1, v154
	v_and_b32_e32 v155, 15, v104
	v_lshl_add_u32 v154, v155, 4, v154
	v_bfe_u32 v155, v104, 4, 2
	v_mul_u32_u24_e32 v155, 0x1c00, v155
	v_add_u32_e32 v154, v154, v155
	v_and_b32_e32 v155, 63, v104
	v_lshlrev_b32_e32 v155, 4, v155
	v_lshrrev_b32_e32 v156, 7, v104
	v_lshl_add_u32 v155, v156, 2, v155
	global_load_dwordx4 v[150:153], v154, s[8:9]
	s_add_u32 s8, s8, 0x7000
	s_addc_u32 s9, s9, 0
	global_load_dwordx4 v[150:153], v154, s[8:9]
	s_add_u32 s8, s8, 0x7000
	s_addc_u32 s9, s9, 0
	global_load_dwordx4 v[150:153], v154, s[8:9]
	s_add_u32 s8, s8, 0x7000
	s_addc_u32 s9, s9, 0
	global_load_dwordx4 v[150:153], v154, s[8:9]
	s_add_u32 s8, s8, 0x7000
	s_addc_u32 s9, s9, 0
	global_load_dwordx4 v[150:153], v154, s[8:9]
	s_add_u32 s8, s8, 0x7000
	s_addc_u32 s9, s9, 0
	global_load_dwordx4 v[150:153], v154, s[8:9]
	s_add_u32 s8, s8, 0x7000
	s_addc_u32 s9, s9, 0
	global_load_dwordx4 v[150:153], v154, s[8:9]
	s_add_u32 s8, s8, 0x7000
	s_addc_u32 s9, s9, 0
	global_load_dwordx4 v[150:153], v154, s[8:9]
	s_add_u32 s8, s8, 0x7000
	s_addc_u32 s9, s9, 0
	global_load_dwordx4 v[150:153], v154, s[8:9]
	s_add_u32 s8, s8, 0x7000
	s_addc_u32 s9, s9, 0
	global_load_dwordx4 v[150:153], v154, s[8:9]
	s_add_u32 s8, s8, 0x7000
	s_addc_u32 s9, s9, 0
	global_load_dwordx4 v[150:153], v154, s[8:9]
	s_add_u32 s8, s8, 0x7000
	s_addc_u32 s9, s9, 0
	global_load_dwordx4 v[150:153], v154, s[8:9]
	s_add_u32 s8, s8, 0x7000
	s_addc_u32 s9, s9, 0
	global_load_dwordx4 v[150:153], v154, s[8:9]
	s_add_u32 s8, s8, 0x7000
	s_addc_u32 s9, s9, 0
	global_load_dwordx4 v[150:153], v154, s[8:9]
	s_add_u32 s8, s8, 0x7000
	s_addc_u32 s9, s9, 0
	global_load_dwordx4 v[150:153], v154, s[8:9]
	s_add_u32 s8, s8, 0x7000
	s_addc_u32 s9, s9, 0
	global_load_dwordx4 v[150:153], v154, s[8:9]
	global_load_dword v150, v155, s[10:11]
	global_load_dword v150, v155, s[20:21]
.Lm1pf_done:
	ds_read_b64_tr_b16 v[0:1], v106
	ds_read_b64_tr_b16 v[2:3], v106 offset:1152
	ds_read_b64_tr_b16 v[4:5], v106 offset:64
	ds_read_b64_tr_b16 v[6:7], v106 offset:1216
	ds_read_b64_tr_b16 v[88:89], v102 offset:18432
	ds_read_b64_tr_b16 v[90:91], v102 offset:19584
	ds_read_b64_tr_b16 v[92:93], v102 offset:18496
	ds_read_b64_tr_b16 v[94:95], v102 offset:19648
	s_waitcnt lgkmcnt(2)
	v_mfma_f32_32x32x16_bf16 v[48:63], v[0:3], v[88:91], 0
	ds_read_b64_tr_b16 v[64:65], v106 offset:4608
	ds_read_b64_tr_b16 v[66:67], v106 offset:5760
	ds_read_b64_tr_b16 v[68:69], v106 offset:4672
	ds_read_b64_tr_b16 v[70:71], v106 offset:5824
	ds_read_b64_tr_b16 v[80:81], v102 offset:23040
	ds_read_b64_tr_b16 v[82:83], v102 offset:24192
	ds_read_b64_tr_b16 v[84:85], v102 offset:23104
	ds_read_b64_tr_b16 v[86:87], v102 offset:24256
	s_mov_b64 s[4:5], 0xd202000
	s_mov_b32 s0, 0
	s_waitcnt lgkmcnt(8)
	v_mfma_f32_32x32x16_bf16 v[32:47], v[0:3], v[92:95], 0
	v_mfma_f32_32x32x16_bf16 v[16:31], v[4:7], v[88:91], 0
	v_mfma_f32_32x32x16_bf16 v[0:15], v[4:7], v[92:95], 0
	s_waitcnt lgkmcnt(2)
	v_mfma_f32_32x32x16_bf16 v[48:63], v[64:67], v[80:83], v[48:63]
	s_waitcnt lgkmcnt(0)
	v_mfma_f32_32x32x16_bf16 v[32:47], v[64:67], v[84:87], v[32:47]
	v_mfma_f32_32x32x16_bf16 v[16:31], v[68:71], v[80:83], v[16:31]
	v_mfma_f32_32x32x16_bf16 v[0:15], v[68:71], v[84:87], v[0:15]
	ds_read_b64_tr_b16 v[64:65], v106 offset:9216
	ds_read_b64_tr_b16 v[66:67], v106 offset:10368
	ds_read_b64_tr_b16 v[68:69], v106 offset:9280
	ds_read_b64_tr_b16 v[70:71], v106 offset:10432
	ds_read_b64_tr_b16 v[72:73], v102 offset:27648
	ds_read_b64_tr_b16 v[74:75], v102 offset:28800
	ds_read_b64_tr_b16 v[76:77], v102 offset:27712
	ds_read_b64_tr_b16 v[78:79], v102 offset:28864
	s_waitcnt lgkmcnt(2)
	v_mfma_f32_32x32x16_bf16 v[48:63], v[64:67], v[72:75], v[48:63]
	s_waitcnt lgkmcnt(0)
	v_mfma_f32_32x32x16_bf16 v[32:47], v[64:67], v[76:79], v[32:47]
	v_mfma_f32_32x32x16_bf16 v[16:31], v[68:71], v[72:75], v[16:31]
	v_mfma_f32_32x32x16_bf16 v[0:15], v[68:71], v[76:79], v[0:15]
	ds_read_b64_tr_b16 v[108:109], v106 offset:13824
	ds_read_b64_tr_b16 v[110:111], v106 offset:14976
	ds_read_b64_tr_b16 v[114:115], v106 offset:13888
	ds_read_b64_tr_b16 v[116:117], v106 offset:15040
	ds_read_b64_tr_b16 v[64:65], v102 offset:32256
	ds_read_b64_tr_b16 v[66:67], v102 offset:33408
	ds_read_b64_tr_b16 v[68:69], v102 offset:32320
	ds_read_b64_tr_b16 v[70:71], v102 offset:33472
	v_lshlrev_b32_e32 v102, 8, v104
	v_and_b32_e32 v102, 0x1f00, v102
	v_lshl_or_b32 v112, v99, 14, v102
	v_lshl_add_u64 v[100:101], v[100:101], 0, v[112:113]
	v_mov_b32_e32 v99, v113
	v_or_b32_e32 v112, 16, v98
	s_waitcnt lgkmcnt(2)
	v_mfma_f32_32x32x16_bf16 v[48:63], v[108:111], v[64:67], v[48:63]
	s_waitcnt lgkmcnt(0)
	v_mfma_f32_32x32x16_bf16 v[32:47], v[108:111], v[68:71], v[32:47]
	v_mfma_f32_32x32x16_bf16 v[16:31], v[114:117], v[64:67], v[16:31]
	v_mfma_f32_32x32x16_bf16 v[0:15], v[114:117], v[68:71], v[0:15]
	v_lshlrev_b32_e32 v112, 1, v98
	v_lshl_add_u64 v[102:103], v[100:101], 0, v[112:113]
	v_lshl_add_u64 v[108:109], v[102:103], 0, s[4:5]
	v_lshl_add_u64 v[102:103], v[102:103], 0, s[56:57]
	s_nop 9
	v_cvt_pk_bf16_f32 v48, v48, v49
	v_cvt_pk_bf16_f32 v49, v50, v51
	v_cvt_pk_bf16_f32 v50, v52, v53
	v_cvt_pk_bf16_f32 v51, v54, v55
	v_cvt_pk_bf16_f32 v52, v56, v57
	v_cvt_pk_bf16_f32 v53, v58, v59
	v_cvt_pk_bf16_f32 v54, v60, v61
	v_cvt_pk_bf16_f32 v55, v62, v63
	v_permlane32_swap_b32_e32 v48, v50
	v_permlane32_swap_b32_e32 v49, v51
	v_permlane32_swap_b32_e32 v52, v54
	v_permlane32_swap_b32_e32 v53, v55
	global_store_dwordx4 v[102:103], v[48:51], off
	global_store_dwordx4 v[102:103], v[52:55], off offset:32
	v_cvt_pk_bf16_f32 v32, v32, v33
	v_cvt_pk_bf16_f32 v33, v34, v35
	v_cvt_pk_bf16_f32 v34, v36, v37
	v_cvt_pk_bf16_f32 v35, v38, v39
	v_cvt_pk_bf16_f32 v36, v40, v41
	v_cvt_pk_bf16_f32 v37, v42, v43
	v_cvt_pk_bf16_f32 v38, v44, v45
	v_cvt_pk_bf16_f32 v39, v46, v47
	v_permlane32_swap_b32_e32 v32, v34
	v_permlane32_swap_b32_e32 v33, v35
	v_permlane32_swap_b32_e32 v36, v38
	v_permlane32_swap_b32_e32 v37, v39
	global_store_dwordx4 v[108:109], v[32:35], off
	global_store_dwordx4 v[108:109], v[36:39], off offset:32
	v_cvt_pk_bf16_f32 v16, v16, v17
	v_cvt_pk_bf16_f32 v17, v18, v19
	v_cvt_pk_bf16_f32 v18, v20, v21
	v_cvt_pk_bf16_f32 v19, v22, v23
	v_cvt_pk_bf16_f32 v20, v24, v25
	v_cvt_pk_bf16_f32 v21, v26, v27
	v_cvt_pk_bf16_f32 v22, v28, v29
	v_cvt_pk_bf16_f32 v23, v30, v31
	v_permlane32_swap_b32_e32 v16, v18
	v_permlane32_swap_b32_e32 v17, v19
	v_permlane32_swap_b32_e32 v20, v22
	v_permlane32_swap_b32_e32 v21, v23
	global_store_dwordx4 v[102:103], v[16:19], off offset:64
	global_store_dwordx4 v[102:103], v[20:23], off offset:96
	v_cvt_pk_bf16_f32 v0, v0, v1
	v_cvt_pk_bf16_f32 v1, v2, v3
	v_cvt_pk_bf16_f32 v2, v4, v5
	v_cvt_pk_bf16_f32 v3, v6, v7
	v_cvt_pk_bf16_f32 v4, v8, v9
	v_cvt_pk_bf16_f32 v5, v10, v11
	v_cvt_pk_bf16_f32 v6, v12, v13
	v_cvt_pk_bf16_f32 v7, v14, v15
	v_permlane32_swap_b32_e32 v0, v2
	v_permlane32_swap_b32_e32 v1, v3
	v_permlane32_swap_b32_e32 v4, v6
	v_permlane32_swap_b32_e32 v5, v7
	global_store_dwordx4 v[108:109], v[0:3], off offset:64
	global_store_dwordx4 v[108:109], v[4:7], off offset:96
	ds_read_b64_tr_b16 v[0:1], v106 offset:128
	ds_read_b64_tr_b16 v[2:3], v106 offset:1280
	ds_read_b64_tr_b16 v[4:5], v106 offset:192
	ds_read_b64_tr_b16 v[6:7], v106 offset:1344
	s_waitcnt lgkmcnt(2)
	v_mfma_f32_32x32x16_bf16 v[32:47], v[0:3], v[92:95], 0
	v_mfma_f32_32x32x16_bf16 v[48:63], v[0:3], v[88:91], 0
	s_waitcnt lgkmcnt(0)
	v_mfma_f32_32x32x16_bf16 v[16:31], v[4:7], v[88:91], 0
	v_mfma_f32_32x32x16_bf16 v[0:15], v[4:7], v[92:95], 0
	ds_read_b64_tr_b16 v[88:89], v106 offset:4736
	ds_read_b64_tr_b16 v[90:91], v106 offset:5888
	ds_read_b64_tr_b16 v[92:93], v106 offset:4800
	ds_read_b64_tr_b16 v[94:95], v106 offset:5952
	s_waitcnt lgkmcnt(2)
	v_mfma_f32_32x32x16_bf16 v[32:47], v[88:91], v[84:87], v[32:47]
	s_waitcnt lgkmcnt(0)
	v_mfma_f32_32x32x16_bf16 v[0:15], v[92:95], v[84:87], v[0:15]
	v_mfma_f32_32x32x16_bf16 v[48:63], v[88:91], v[80:83], v[48:63]
	v_mfma_f32_32x32x16_bf16 v[16:31], v[92:95], v[80:83], v[16:31]
	ds_read_b64_tr_b16 v[80:81], v106 offset:9344
	ds_read_b64_tr_b16 v[82:83], v106 offset:10496
	ds_read_b64_tr_b16 v[84:85], v106 offset:9408
	ds_read_b64_tr_b16 v[86:87], v106 offset:10560
	s_waitcnt lgkmcnt(2)
	v_mfma_f32_32x32x16_bf16 v[32:47], v[80:83], v[76:79], v[32:47]
	s_waitcnt lgkmcnt(0)
	v_mfma_f32_32x32x16_bf16 v[0:15], v[84:87], v[76:79], v[0:15]
	v_mfma_f32_32x32x16_bf16 v[48:63], v[80:83], v[72:75], v[48:63]
	v_mfma_f32_32x32x16_bf16 v[16:31], v[84:87], v[72:75], v[16:31]
	ds_read_b64_tr_b16 v[72:73], v106 offset:13952
	ds_read_b64_tr_b16 v[74:75], v106 offset:15104
	ds_read_b64_tr_b16 v[76:77], v106 offset:14016
	ds_read_b64_tr_b16 v[78:79], v106 offset:15168
	s_waitcnt lgkmcnt(2)
	v_mfma_f32_32x32x16_bf16 v[32:47], v[72:75], v[68:71], v[32:47]
	s_waitcnt lgkmcnt(0)
	v_mfma_f32_32x32x16_bf16 v[0:15], v[76:79], v[68:71], v[0:15]
	v_mfma_f32_32x32x16_bf16 v[48:63], v[72:75], v[64:67], v[48:63]
	v_mfma_f32_32x32x16_bf16 v[16:31], v[76:79], v[64:67], v[16:31]
	s_nop 15
	v_cvt_pk_bf16_f32 v48, v48, v49
	v_cvt_pk_bf16_f32 v49, v50, v51
	v_cvt_pk_bf16_f32 v50, v52, v53
	v_cvt_pk_bf16_f32 v51, v54, v55
	v_cvt_pk_bf16_f32 v52, v56, v57
	v_cvt_pk_bf16_f32 v53, v58, v59
	v_cvt_pk_bf16_f32 v54, v60, v61
	v_cvt_pk_bf16_f32 v55, v62, v63
	v_permlane32_swap_b32_e32 v48, v50
	v_permlane32_swap_b32_e32 v49, v51
	v_permlane32_swap_b32_e32 v52, v54
	v_permlane32_swap_b32_e32 v53, v55
	global_store_dwordx4 v[102:103], v[48:51], off offset:128
	global_store_dwordx4 v[102:103], v[52:55], off offset:160
	v_cvt_pk_bf16_f32 v32, v32, v33
	v_cvt_pk_bf16_f32 v33, v34, v35
	v_cvt_pk_bf16_f32 v34, v36, v37
	v_cvt_pk_bf16_f32 v35, v38, v39
	v_cvt_pk_bf16_f32 v36, v40, v41
	v_cvt_pk_bf16_f32 v37, v42, v43
	v_cvt_pk_bf16_f32 v38, v44, v45
	v_cvt_pk_bf16_f32 v39, v46, v47
	v_permlane32_swap_b32_e32 v32, v34
	v_permlane32_swap_b32_e32 v33, v35
	v_permlane32_swap_b32_e32 v36, v38
	v_permlane32_swap_b32_e32 v37, v39
	global_store_dwordx4 v[108:109], v[32:35], off offset:128
	global_store_dwordx4 v[108:109], v[36:39], off offset:160
	v_cvt_pk_bf16_f32 v16, v16, v17
	v_cvt_pk_bf16_f32 v17, v18, v19
	v_cvt_pk_bf16_f32 v18, v20, v21
	v_cvt_pk_bf16_f32 v19, v22, v23
	v_cvt_pk_bf16_f32 v20, v24, v25
	v_cvt_pk_bf16_f32 v21, v26, v27
	v_cvt_pk_bf16_f32 v22, v28, v29
	v_cvt_pk_bf16_f32 v23, v30, v31
	v_permlane32_swap_b32_e32 v16, v18
	v_permlane32_swap_b32_e32 v17, v19
	v_permlane32_swap_b32_e32 v20, v22
	v_permlane32_swap_b32_e32 v21, v23
	global_store_dwordx4 v[102:103], v[16:19], off offset:192
	global_store_dwordx4 v[102:103], v[20:23], off offset:224
	v_cvt_pk_bf16_f32 v0, v0, v1
	v_cvt_pk_bf16_f32 v1, v2, v3
	v_cvt_pk_bf16_f32 v2, v4, v5
	v_cvt_pk_bf16_f32 v3, v6, v7
	v_cvt_pk_bf16_f32 v4, v8, v9
	v_cvt_pk_bf16_f32 v5, v10, v11
	v_cvt_pk_bf16_f32 v6, v12, v13
	v_cvt_pk_bf16_f32 v7, v14, v15
	v_permlane32_swap_b32_e32 v0, v2
	v_permlane32_swap_b32_e32 v1, v3
	v_permlane32_swap_b32_e32 v4, v6
	v_permlane32_swap_b32_e32 v5, v7
	global_store_dwordx4 v[108:109], v[0:3], off offset:192
	global_store_dwordx4 v[108:109], v[4:7], off offset:224
	s_nop 1
	v_and_b32_e32 v0, 0x7f, v104
	v_lshl_add_u32 v1, v0, 1, v105
	v_mov_b32_e32 v2, 0
